# RNN unit tail: the eight y reads and the grid-size scalar load issued together, one wait instead of five serialized ones
# speedup vs baseline: 1.0068x; 1.0068x over previous
.LBB0_84:
	s_waitcnt lgkmcnt(0)
	s_barrier
	v_add_u32_e32 v0, v171, v228
	v_readlane_b32 s20, v253, 1
	v_readlane_b32 s21, v253, 2
	ds_read_u16 v2, v0
	ds_read_u16 v3, v0 offset:272
	ds_read_u16 v8, v0 offset:544
	ds_read_u16 v4, v0 offset:816
	ds_read_u16 v9, v0 offset:1088
	ds_read_u16 v5, v0 offset:1360
	ds_read_u16 v10, v0 offset:1632
	ds_read_u16 v11, v0 offset:1904
	v_lshlrev_b64 v[6:7], 12, v[168:169]
	v_lshl_add_u64 v[6:7], s[0:1], 0, v[6:7]
	v_mov_b32_e32 v171, v1
	v_lshl_add_u64 v[6:7], v[6:7], 0, v[170:171]
	s_load_dword s23, s[20:21], 0x10
	s_mov_b32 s0, 0xf80000
	v_add_co_u32_e32 v6, vcc, s0, v6
	s_nop 0
	v_addc_co_u32_e32 v7, vcc, 0, v7, vcc
	s_waitcnt lgkmcnt(0)
	v_lshl_or_b32 v2, v3, 16, v2
	v_lshl_or_b32 v3, v4, 16, v8
	v_lshl_or_b32 v4, v5, 16, v9
	v_lshl_or_b32 v5, v11, 16, v10
	global_store_dwordx4 v[6:7], v[2:5], off sc1
	s_waitcnt lgkmcnt(0)
	s_barrier
	s_lshr_b32 s0, s23, 16
	s_cmp_lg_u32 s0, 0
	s_cselect_b64 s[0:1], -1, 0
	s_cmp_lg_u64 s[0:1], 0
	s_addc_u32 s22, s22, s94
	s_cmpk_gt_i32 s22, 0xff
	s_cbranch_scc1 .Lmix_rnn_done
